# final RMSNorm prompt loop: final_g hoisted to registers, 10 loads per iteration in flight, stores back to back
# baseline (speedup 1.0000x reference)
.LBB0_1168:
	v_readlane_b32 s18, v255, 4
	v_readlane_b32 s20, v254, 63
	s_cmp_lt_i32 s2, 32
	v_readlane_b32 s17, v253, 63
	v_readlane_b32 s19, v255, 5
	v_readlane_b32 s21, v255, 0
	s_cbranch_scc1 .LBB0_1173
	v_mov_b32_e32 v6, v232
	s_add_i32 s0, s17, 0xfffffe00
	v_ashrrev_i32_e32 v0, 5, v6
	v_and_b32_e32 v0, -2, v0
	v_add_u32_e32 v0, s0, v0
	s_movk_i32 s0, 0x4000
	v_cmp_gt_i32_e32 vcc, s0, v0
	s_and_saveexec_b64 s[2:3], vcc
	s_cbranch_execz .LBB0_1172
	s_waitcnt lgkmcnt(0)
	v_lshlrev_b32_e32 v1, 4, v6
	v_and_b32_e32 v2, 0x3f0, v1
	v_ashrrev_i32_e32 v1, 31, v0
	v_lshlrev_b64 v[8:9], 12, v[0:1]
	v_and_b32_e32 v10, 63, v6
	s_add_i32 s4, s20, 0xfffffe00
	v_lshl_or_b32 v8, v10, 4, v8
	v_mov_b32_e32 v3, 0
	s_ashr_i32 s5, s4, 31
	v_lshl_add_u64 v[6:7], s[26:27], 0, v[8:9]
	s_mov_b64 s[0:1], 0x1000
	v_lshlrev_b64 v[8:9], 11, v[0:1]
	v_lshl_add_u64 v[2:3], s[24:25], 0, v[2:3]
	v_lshlrev_b64 v[4:5], 2, v[0:1]
	s_lshl_b64 s[6:7], s[4:5], 2
	v_lshl_add_u64 v[6:7], v[6:7], 0, s[0:1]
	s_lshl_b64 s[38:39], s[4:5], 12
	v_lshl_or_b32 v8, v10, 3, v8
	s_lshl_b64 s[40:41], s[4:5], 11
	s_mov_b64 s[42:43], 0
	v_mov_b32_e32 v1, 0x358637bd
	s_mov_b32 s5, 0x800000
	global_load_dwordx4 v[104:107], v[2:3], off
	global_load_dwordx4 v[108:111], v[2:3], off offset:1024
	global_load_dwordx4 v[112:115], v[2:3], off offset:2048
	global_load_dwordx4 v[116:119], v[2:3], off offset:3072
.LBB0_1171:
	v_lshl_add_u64 v[10:11], s[84:85], 0, v[8:9]
	v_lshl_add_u64 v[12:13], s[84:85], 0, v[4:5]
	s_mov_b32 s0, 0x8d6c000
	v_add_co_u32_e32 v14, vcc, 0x8e38000, v10
	v_add_co_u32_e64 v16, s[0:1], s0, v12
	s_nop 0
	v_addc_co_u32_e32 v15, vcc, 0, v11, vcc
	v_addc_co_u32_e64 v17, s[0:1], 0, v13, s[0:1]
	global_load_dword v32, v[16:17], off
	global_load_dword v33, v[16:17], off offset:4
	global_load_dwordx2 v[18:19], v[14:15], off
	global_load_dwordx2 v[20:21], v[14:15], off offset:512
	global_load_dwordx2 v[22:23], v[14:15], off offset:1024
	global_load_dwordx2 v[24:25], v[14:15], off offset:1536
	global_load_dwordx2 v[26:27], v[14:15], off offset:2048
	global_load_dwordx2 v[28:29], v[14:15], off offset:2560
	global_load_dwordx2 v[30:31], v[14:15], off offset:3072
	s_nop 0
	global_load_dwordx2 v[14:15], v[14:15], off offset:3584
	v_add_u32_e32 v0, s4, v0
	s_movk_i32 s0, 0x3fff
	v_lshl_add_u64 v[4:5], v[4:5], 0, s[6:7]
	v_lshl_add_u64 v[8:9], v[8:9], 0, s[40:41]
	v_cmp_lt_i32_e32 vcc, s0, v0
	s_or_b64 s[42:43], vcc, s[42:43]
	s_waitcnt vmcnt(0)
	v_fmamk_f32 v34, v32, 0x3a800000, v1
	v_fmamk_f32 v36, v33, 0x3a800000, v1
	v_mul_f32_e32 v35, 0x4b800000, v34
	v_mul_f32_e32 v37, 0x4b800000, v36
	v_cmp_gt_f32_e32 vcc, s5, v34
	v_cmp_gt_f32_e64 s[0:1], s5, v36
	s_nop 1
	v_cndmask_b32_e32 v34, v34, v35, vcc
	v_cndmask_b32_e64 v36, v36, v37, s[0:1]
	v_rsq_f32_e32 v34, v34
	v_rsq_f32_e32 v36, v36
	s_nop 0
	v_mul_f32_e32 v35, 0x45800000, v34
	v_mul_f32_e32 v37, 0x45800000, v36
	v_cndmask_b32_e32 v34, v34, v35, vcc
	v_cndmask_b32_e64 v36, v36, v37, s[0:1]
	v_lshlrev_b32_e32 v120, 16, v18
	v_and_b32_e32 v121, 0xffff0000, v18
	v_lshlrev_b32_e32 v122, 16, v19
	v_and_b32_e32 v123, 0xffff0000, v19
	v_pk_mul_f32 v[120:121], v[34:35], v[120:121] op_sel_hi:[0,1]
	v_pk_mul_f32 v[122:123], v[34:35], v[122:123] op_sel_hi:[0,1]
	v_pk_mul_f32 v[120:121], v[104:105], v[120:121]
	v_pk_mul_f32 v[122:123], v[106:107], v[122:123]
	global_store_dwordx4 v[6:7], v[120:123], off offset:-4096
	v_lshlrev_b32_e32 v124, 16, v20
	v_and_b32_e32 v125, 0xffff0000, v20
	v_lshlrev_b32_e32 v126, 16, v21
	v_and_b32_e32 v127, 0xffff0000, v21
	v_pk_mul_f32 v[124:125], v[34:35], v[124:125] op_sel_hi:[0,1]
	v_pk_mul_f32 v[126:127], v[34:35], v[126:127] op_sel_hi:[0,1]
	v_pk_mul_f32 v[124:125], v[108:109], v[124:125]
	v_pk_mul_f32 v[126:127], v[110:111], v[126:127]
	global_store_dwordx4 v[6:7], v[124:127], off offset:-3072
	v_lshlrev_b32_e32 v128, 16, v22
	v_and_b32_e32 v129, 0xffff0000, v22
	v_lshlrev_b32_e32 v130, 16, v23
	v_and_b32_e32 v131, 0xffff0000, v23
	v_pk_mul_f32 v[128:129], v[34:35], v[128:129] op_sel_hi:[0,1]
	v_pk_mul_f32 v[130:131], v[34:35], v[130:131] op_sel_hi:[0,1]
	v_pk_mul_f32 v[128:129], v[112:113], v[128:129]
	v_pk_mul_f32 v[130:131], v[114:115], v[130:131]
	global_store_dwordx4 v[6:7], v[128:131], off offset:-2048
	v_lshlrev_b32_e32 v132, 16, v24
	v_and_b32_e32 v133, 0xffff0000, v24
	v_lshlrev_b32_e32 v134, 16, v25
	v_and_b32_e32 v135, 0xffff0000, v25
	v_pk_mul_f32 v[132:133], v[34:35], v[132:133] op_sel_hi:[0,1]
	v_pk_mul_f32 v[134:135], v[34:35], v[134:135] op_sel_hi:[0,1]
	v_pk_mul_f32 v[132:133], v[116:117], v[132:133]
	v_pk_mul_f32 v[134:135], v[118:119], v[134:135]
	global_store_dwordx4 v[6:7], v[132:135], off offset:-1024
	v_lshlrev_b32_e32 v136, 16, v26
	v_and_b32_e32 v137, 0xffff0000, v26
	v_lshlrev_b32_e32 v138, 16, v27
	v_and_b32_e32 v139, 0xffff0000, v27
	v_pk_mul_f32 v[136:137], v[36:37], v[136:137] op_sel_hi:[0,1]
	v_pk_mul_f32 v[138:139], v[36:37], v[138:139] op_sel_hi:[0,1]
	v_pk_mul_f32 v[136:137], v[104:105], v[136:137]
	v_pk_mul_f32 v[138:139], v[106:107], v[138:139]
	global_store_dwordx4 v[6:7], v[136:139], off
	v_lshlrev_b32_e32 v140, 16, v28
	v_and_b32_e32 v141, 0xffff0000, v28
	v_lshlrev_b32_e32 v142, 16, v29
	v_and_b32_e32 v143, 0xffff0000, v29
	v_pk_mul_f32 v[140:141], v[36:37], v[140:141] op_sel_hi:[0,1]
	v_pk_mul_f32 v[142:143], v[36:37], v[142:143] op_sel_hi:[0,1]
	v_pk_mul_f32 v[140:141], v[108:109], v[140:141]
	v_pk_mul_f32 v[142:143], v[110:111], v[142:143]
	global_store_dwordx4 v[6:7], v[140:143], off offset:1024
	v_lshlrev_b32_e32 v144, 16, v30
	v_and_b32_e32 v145, 0xffff0000, v30
	v_lshlrev_b32_e32 v146, 16, v31
	v_and_b32_e32 v147, 0xffff0000, v31
	v_pk_mul_f32 v[144:145], v[36:37], v[144:145] op_sel_hi:[0,1]
	v_pk_mul_f32 v[146:147], v[36:37], v[146:147] op_sel_hi:[0,1]
	v_pk_mul_f32 v[144:145], v[112:113], v[144:145]
	v_pk_mul_f32 v[146:147], v[114:115], v[146:147]
	global_store_dwordx4 v[6:7], v[144:147], off offset:2048
	v_lshlrev_b32_e32 v148, 16, v14
	v_and_b32_e32 v149, 0xffff0000, v14
	v_lshlrev_b32_e32 v150, 16, v15
	v_and_b32_e32 v151, 0xffff0000, v15
	v_pk_mul_f32 v[148:149], v[36:37], v[148:149] op_sel_hi:[0,1]
	v_pk_mul_f32 v[150:151], v[36:37], v[150:151] op_sel_hi:[0,1]
	v_pk_mul_f32 v[148:149], v[116:117], v[148:149]
	v_pk_mul_f32 v[150:151], v[118:119], v[150:151]
	global_store_dwordx4 v[6:7], v[148:151], off offset:3072
	v_lshl_add_u64 v[6:7], v[6:7], 0, s[38:39]
	s_andn2_b64 exec, exec, s[42:43]
	s_cbranch_execnz .LBB0_1171
